# base9 + per-unit vmcnt(0) loop-preheader flush removed in the 4 GEMM instances that had it
# speedup vs baseline: 1.0050x; 1.0050x over previous
; #define PG8_BAR __builtin_amdgcn_s_barrier()
;     ...
; #pragma unroll
;         for (int a = 0; a < 2; ++a)
; #pragma unroll
;             for (int b = 0; b < 2; ++b)
; #pragma unroll
;                 for (int m = 0; m < 4; ++m)
; #pragma unroll
;                     for (int n = 0; n < 2; ++n) acc[a][b][m][n] = (f32x4){0.f, 0.f, 0.f, 0.f};
;         cur = nxt; cA = nA; cB = nB; ++ui;
;         if constexpr (GATHER) {
; #pragma unroll
;             for (int i = 0; i < 2; ++i) { gc0[i] = (unsigned)gn0r[i] * (unsigned)(g.lda * ESZ) + gC2[i]; gc1[i] = (unsigned)gn1r[i] * (unsigned)(g.lda * ESZ) + gC2[i]; } }
;         if constexpr (ALIGN_EPI) { if (wr == 1) PG8_BAR; }
.LBB0_654:
	s_add_u32 s39, s2, 0x100
	s_addc_u32 s40, s3, 0
	s_add_u32 s0, s0, 0x40080
	v_mov_b32_e32 v52, 0
	s_addc_u32 s1, s1, 0
	s_mov_b32 s41, -2
	v_mov_b32_e32 v53, v52
	v_mov_b32_e32 v54, v52
	v_mov_b32_e32 v55, v52
	v_mov_b32_e32 v56, v52
	v_mov_b32_e32 v57, v52
	v_mov_b32_e32 v58, v52
	v_mov_b32_e32 v59, v52
	v_mov_b32_e32 v68, v52
	v_mov_b32_e32 v69, v52
	v_mov_b32_e32 v70, v52
	v_mov_b32_e32 v71, v52
	v_mov_b32_e32 v72, v52
	v_mov_b32_e32 v73, v52
	v_mov_b32_e32 v74, v52
	v_mov_b32_e32 v75, v52
	v_mov_b32_e32 v10, v52
	v_mov_b32_e32 v11, v52
	v_mov_b32_e32 v12, v52
	v_mov_b32_e32 v13, v52
	v_mov_b32_e32 v18, v52
	v_mov_b32_e32 v19, v52
	v_mov_b32_e32 v20, v52
	v_mov_b32_e32 v21, v52
	v_mov_b32_e32 v42, v52
	v_mov_b32_e32 v43, v52
	v_mov_b32_e32 v44, v52
	v_mov_b32_e32 v45, v52
	v_mov_b32_e32 v46, v52
	v_mov_b32_e32 v47, v52
	v_mov_b32_e32 v48, v52
	v_mov_b32_e32 v49, v52
	v_mov_b32_e32 v60, v52
	v_mov_b32_e32 v61, v52
	v_mov_b32_e32 v62, v52
	v_mov_b32_e32 v63, v52
	v_mov_b32_e32 v64, v52
	v_mov_b32_e32 v65, v52
	v_mov_b32_e32 v66, v52
	v_mov_b32_e32 v67, v52
	v_mov_b32_e32 v76, v52
	v_mov_b32_e32 v77, v52
	v_mov_b32_e32 v78, v52
	v_mov_b32_e32 v79, v52
	v_mov_b32_e32 v80, v52
	v_mov_b32_e32 v81, v52
	v_mov_b32_e32 v82, v52
	v_mov_b32_e32 v83, v52
	v_mov_b32_e32 v84, v52
	v_mov_b32_e32 v85, v52
	v_mov_b32_e32 v86, v52
	v_mov_b32_e32 v87, v52
	v_mov_b32_e32 v88, v52
	v_mov_b32_e32 v89, v52
	v_mov_b32_e32 v90, v52
	v_mov_b32_e32 v91, v52
	v_mov_b32_e32 v100, v52
	v_mov_b32_e32 v101, v52
	v_mov_b32_e32 v102, v52
	v_mov_b32_e32 v103, v52
	v_mov_b32_e32 v104, v52
	v_mov_b32_e32 v105, v52
	v_mov_b32_e32 v106, v52
	v_mov_b32_e32 v107, v52
	v_mov_b32_e32 v116, v52
	v_mov_b32_e32 v117, v52
	v_mov_b32_e32 v118, v52
	v_mov_b32_e32 v119, v52
	v_mov_b32_e32 v120, v52
	v_mov_b32_e32 v121, v52
	v_mov_b32_e32 v122, v52
	v_mov_b32_e32 v123, v52
	v_mov_b32_e32 v132, v52
	v_mov_b32_e32 v133, v52
	v_mov_b32_e32 v134, v52
	v_mov_b32_e32 v135, v52
	v_mov_b32_e32 v136, v52
	v_mov_b32_e32 v137, v52
	v_mov_b32_e32 v138, v52
	v_mov_b32_e32 v139, v52
	v_mov_b32_e32 v92, v52
	v_mov_b32_e32 v93, v52
	v_mov_b32_e32 v94, v52
	v_mov_b32_e32 v95, v52
	v_mov_b32_e32 v96, v52
	v_mov_b32_e32 v97, v52
	v_mov_b32_e32 v98, v52
	v_mov_b32_e32 v99, v52
	v_mov_b32_e32 v108, v52
	v_mov_b32_e32 v109, v52
	v_mov_b32_e32 v110, v52
	v_mov_b32_e32 v111, v52
	v_mov_b32_e32 v112, v52
	v_mov_b32_e32 v113, v52
	v_mov_b32_e32 v114, v52
	v_mov_b32_e32 v115, v52
	v_mov_b32_e32 v124, v52
	v_mov_b32_e32 v125, v52
	v_mov_b32_e32 v126, v52
	v_mov_b32_e32 v127, v52
	v_mov_b32_e32 v128, v52
	v_mov_b32_e32 v129, v52
	v_mov_b32_e32 v130, v52
	v_mov_b32_e32 v131, v52
	v_mov_b32_e32 v140, v52
	v_mov_b32_e32 v141, v52
	v_mov_b32_e32 v142, v52
	v_mov_b32_e32 v143, v52
	v_mov_b32_e32 v144, v52
	v_mov_b32_e32 v145, v52
	v_mov_b32_e32 v146, v52
	v_mov_b32_e32 v147, v52
	v_mov_b32_e32 v38, v52
	v_mov_b32_e32 v39, v52
	v_mov_b32_e32 v40, v52
	v_mov_b32_e32 v41, v52
	v_mov_b32_e32 v30, v52
	v_mov_b32_e32 v31, v52
	v_mov_b32_e32 v32, v52
	v_mov_b32_e32 v33, v52
	v_mov_b32_e32 v6, v52
	v_mov_b32_e32 v7, v52
	v_mov_b32_e32 v8, v52
	v_mov_b32_e32 v9, v52
	v_mov_b32_e32 v2, v52
	v_mov_b32_e32 v3, v52
	v_mov_b32_e32 v4, v52
	v_mov_b32_e32 v5, v52
	s_nop 0

; #define PG8_BAR __builtin_amdgcn_s_barrier()
;     ...
; #pragma unroll
;         for (int a = 0; a < 2; ++a)
; #pragma unroll
;             for (int b = 0; b < 2; ++b)
; #pragma unroll
;                 for (int m = 0; m < 4; ++m)
; #pragma unroll
;                     for (int n = 0; n < 2; ++n) acc[a][b][m][n] = (f32x4){0.f, 0.f, 0.f, 0.f};
;         cur = nxt; cA = nA; cB = nB; ++ui;
;         if constexpr (GATHER) {
; #pragma unroll
;             for (int i = 0; i < 2; ++i) { gc0[i] = (unsigned)gn0r[i] * (unsigned)(g.lda * ESZ) + gC2[i]; gc1[i] = (unsigned)gn1r[i] * (unsigned)(g.lda * ESZ) + gC2[i]; } }
;         if constexpr (ALIGN_EPI) { if (wr == 1) PG8_BAR; }
.LBB0_1855:
	s_add_u32 s13, s14, 0x100
	s_addc_u32 s16, s15, 0
	s_add_u32 s48, s2, 0x20080
	v_mov_b32_e32 v68, 0
	s_addc_u32 s49, s3, 0
	s_mov_b32 s17, -2
	v_mov_b32_e32 v69, v68
	v_mov_b32_e32 v70, v68
	v_mov_b32_e32 v71, v68
	v_mov_b32_e32 v72, v68
	v_mov_b32_e32 v73, v68
	v_mov_b32_e32 v74, v68
	v_mov_b32_e32 v75, v68
	s_nop 0
	v_mov_b32_e32 v84, v68
	v_mov_b32_e32 v85, v68
	v_mov_b32_e32 v86, v68
	v_mov_b32_e32 v87, v68
	v_mov_b32_e32 v88, v68
	v_mov_b32_e32 v89, v68
	v_mov_b32_e32 v90, v68
	v_mov_b32_e32 v91, v68
	v_mov_b32_e32 v42, v68
	v_mov_b32_e32 v43, v68
	v_mov_b32_e32 v44, v68
	v_mov_b32_e32 v45, v68
	v_mov_b32_e32 v46, v68
	v_mov_b32_e32 v47, v68
	v_mov_b32_e32 v48, v68
	v_mov_b32_e32 v49, v68
	v_mov_b32_e32 v60, v68
	v_mov_b32_e32 v61, v68
	v_mov_b32_e32 v62, v68
	v_mov_b32_e32 v63, v68
	v_mov_b32_e32 v64, v68
	v_mov_b32_e32 v65, v68
	v_mov_b32_e32 v66, v68
	v_mov_b32_e32 v67, v68
	v_mov_b32_e32 v76, v68
	v_mov_b32_e32 v77, v68
	v_mov_b32_e32 v78, v68
	v_mov_b32_e32 v79, v68
	v_mov_b32_e32 v80, v68
	v_mov_b32_e32 v81, v68
	v_mov_b32_e32 v82, v68
	v_mov_b32_e32 v83, v68
	v_mov_b32_e32 v92, v68
	v_mov_b32_e32 v93, v68
	v_mov_b32_e32 v94, v68
	v_mov_b32_e32 v95, v68
	v_mov_b32_e32 v96, v68
	v_mov_b32_e32 v97, v68
	v_mov_b32_e32 v98, v68
	v_mov_b32_e32 v99, v68
	v_mov_b32_e32 v100, v68
	v_mov_b32_e32 v101, v68
	v_mov_b32_e32 v102, v68
	v_mov_b32_e32 v103, v68
	v_mov_b32_e32 v104, v68
	v_mov_b32_e32 v105, v68
	v_mov_b32_e32 v106, v68
	v_mov_b32_e32 v107, v68
	v_mov_b32_e32 v116, v68
	v_mov_b32_e32 v117, v68
	v_mov_b32_e32 v118, v68
	v_mov_b32_e32 v119, v68
	v_mov_b32_e32 v120, v68
	v_mov_b32_e32 v121, v68
	v_mov_b32_e32 v122, v68
	v_mov_b32_e32 v123, v68
	v_mov_b32_e32 v132, v68
	v_mov_b32_e32 v133, v68
	v_mov_b32_e32 v134, v68
	v_mov_b32_e32 v135, v68
	v_mov_b32_e32 v136, v68
	v_mov_b32_e32 v137, v68
	v_mov_b32_e32 v138, v68
	v_mov_b32_e32 v139, v68
	v_mov_b32_e32 v148, v68
	v_mov_b32_e32 v149, v68
	v_mov_b32_e32 v150, v68
	v_mov_b32_e32 v151, v68
	v_mov_b32_e32 v152, v68
	v_mov_b32_e32 v153, v68
	v_mov_b32_e32 v154, v68
	v_mov_b32_e32 v155, v68
	v_mov_b32_e32 v108, v68
	v_mov_b32_e32 v109, v68
	v_mov_b32_e32 v110, v68
	v_mov_b32_e32 v111, v68
	v_mov_b32_e32 v112, v68
	v_mov_b32_e32 v113, v68
	v_mov_b32_e32 v114, v68
	v_mov_b32_e32 v115, v68
	v_mov_b32_e32 v124, v68
	v_mov_b32_e32 v125, v68
	v_mov_b32_e32 v126, v68
	v_mov_b32_e32 v127, v68
	v_mov_b32_e32 v128, v68
	v_mov_b32_e32 v129, v68
	v_mov_b32_e32 v130, v68
	v_mov_b32_e32 v131, v68
	v_mov_b32_e32 v140, v68
	v_mov_b32_e32 v141, v68
	v_mov_b32_e32 v142, v68
	v_mov_b32_e32 v143, v68
	v_mov_b32_e32 v144, v68
	v_mov_b32_e32 v145, v68
	v_mov_b32_e32 v146, v68
	v_mov_b32_e32 v147, v68
	v_mov_b32_e32 v156, v68
	v_mov_b32_e32 v157, v68
	v_mov_b32_e32 v158, v68
	v_mov_b32_e32 v159, v68
	v_mov_b32_e32 v160, v68
	v_mov_b32_e32 v161, v68
	v_mov_b32_e32 v162, v68
	v_mov_b32_e32 v163, v68
	v_mov_b32_e32 v56, v68
	v_mov_b32_e32 v57, v68
	v_mov_b32_e32 v58, v68
	v_mov_b32_e32 v59, v68
	v_mov_b32_e32 v52, v68
	v_mov_b32_e32 v53, v68
	v_mov_b32_e32 v54, v68
	v_mov_b32_e32 v55, v68
	v_mov_b32_e32 v38, v68
	v_mov_b32_e32 v39, v68
	v_mov_b32_e32 v40, v68
	v_mov_b32_e32 v41, v68
	v_mov_b32_e32 v34, v68
	v_mov_b32_e32 v35, v68
	v_mov_b32_e32 v36, v68
	v_mov_b32_e32 v37, v68

; #define PG8_BAR __builtin_amdgcn_s_barrier()
;     ...
; #pragma unroll
;         for (int a = 0; a < 2; ++a)
; #pragma unroll
;             for (int b = 0; b < 2; ++b)
; #pragma unroll
;                 for (int m = 0; m < 4; ++m)
; #pragma unroll
;                     for (int n = 0; n < 2; ++n) acc[a][b][m][n] = (f32x4){0.f, 0.f, 0.f, 0.f};
;         cur = nxt; cA = nA; cB = nB; ++ui;
;         if constexpr (GATHER) {
; #pragma unroll
;             for (int i = 0; i < 2; ++i) { gc0[i] = (unsigned)gn0r[i] * (unsigned)(g.lda * ESZ) + gC2[i]; gc1[i] = (unsigned)gn1r[i] * (unsigned)(g.lda * ESZ) + gC2[i]; } }
;         if constexpr (ALIGN_EPI) { if (wr == 1) PG8_BAR; }
.LBB0_2401:
	s_add_u32 s41, s2, 0x100
	s_addc_u32 s53, s3, 0
	s_add_u32 s48, s14, 0x80
	v_mov_b32_e32 v34, 0
	v_mov_b32_e32 v171, v51
	v_mov_b32_e32 v175, v51
	s_addc_u32 s49, s15, 0
	s_mov_b32 s54, -2
	v_mov_b32_e32 v35, v34
	v_mov_b32_e32 v36, v34
	v_mov_b32_e32 v37, v34
	v_mov_b32_e32 v42, v34
	v_mov_b32_e32 v43, v34
	v_mov_b32_e32 v44, v34
	v_mov_b32_e32 v45, v34
	v_mov_b32_e32 v52, v34
	v_mov_b32_e32 v53, v34
	v_mov_b32_e32 v54, v34
	v_mov_b32_e32 v55, v34
	v_mov_b32_e32 v60, v34
	v_mov_b32_e32 v61, v34
	v_mov_b32_e32 v62, v34
	v_mov_b32_e32 v63, v34
	v_mov_b32_e32 v68, v34
	v_mov_b32_e32 v69, v34
	v_mov_b32_e32 v70, v34
	v_mov_b32_e32 v71, v34
	v_mov_b32_e32 v76, v34
	v_mov_b32_e32 v77, v34
	v_mov_b32_e32 v78, v34
	v_mov_b32_e32 v79, v34
	v_mov_b32_e32 v84, v34
	v_mov_b32_e32 v85, v34
	v_mov_b32_e32 v86, v34
	v_mov_b32_e32 v87, v34
	v_mov_b32_e32 v92, v34
	v_mov_b32_e32 v93, v34
	v_mov_b32_e32 v94, v34
	v_mov_b32_e32 v95, v34
	v_mov_b32_e32 v38, v34
	v_mov_b32_e32 v39, v34
	v_mov_b32_e32 v40, v34
	v_mov_b32_e32 v41, v34
	v_mov_b32_e32 v46, v34
	v_mov_b32_e32 v47, v34
	v_mov_b32_e32 v48, v34
	v_mov_b32_e32 v49, v34
	v_mov_b32_e32 v56, v34
	v_mov_b32_e32 v57, v34
	v_mov_b32_e32 v58, v34
	v_mov_b32_e32 v59, v34
	v_mov_b32_e32 v64, v34
	v_mov_b32_e32 v65, v34
	v_mov_b32_e32 v66, v34
	v_mov_b32_e32 v67, v34
	v_mov_b32_e32 v72, v34
	v_mov_b32_e32 v73, v34
	v_mov_b32_e32 v74, v34
	v_mov_b32_e32 v75, v34
	v_mov_b32_e32 v80, v34
	v_mov_b32_e32 v81, v34
	v_mov_b32_e32 v82, v34
	v_mov_b32_e32 v83, v34
	v_mov_b32_e32 v88, v34
	v_mov_b32_e32 v89, v34
	v_mov_b32_e32 v90, v34
	v_mov_b32_e32 v91, v34
	v_mov_b32_e32 v96, v34
	v_mov_b32_e32 v97, v34
	v_mov_b32_e32 v98, v34
	v_mov_b32_e32 v99, v34
	v_mov_b32_e32 v100, v34
	v_mov_b32_e32 v101, v34
	v_mov_b32_e32 v102, v34
	v_mov_b32_e32 v103, v34
	v_mov_b32_e32 v108, v34
	v_mov_b32_e32 v109, v34
	v_mov_b32_e32 v110, v34
	v_mov_b32_e32 v111, v34
	v_mov_b32_e32 v116, v34
	v_mov_b32_e32 v117, v34
	v_mov_b32_e32 v118, v34
	v_mov_b32_e32 v119, v34
	v_mov_b32_e32 v124, v34
	v_mov_b32_e32 v125, v34
	v_mov_b32_e32 v126, v34
	v_mov_b32_e32 v127, v34
	v_mov_b32_e32 v132, v34
	v_mov_b32_e32 v133, v34
	v_mov_b32_e32 v134, v34
	v_mov_b32_e32 v135, v34
	v_mov_b32_e32 v140, v34
	v_mov_b32_e32 v141, v34
	v_mov_b32_e32 v142, v34
	v_mov_b32_e32 v143, v34
	v_mov_b32_e32 v148, v34
	v_mov_b32_e32 v149, v34
	v_mov_b32_e32 v150, v34
	v_mov_b32_e32 v151, v34
	v_mov_b32_e32 v156, v34
	v_mov_b32_e32 v157, v34
	v_mov_b32_e32 v158, v34
	v_mov_b32_e32 v159, v34
	v_mov_b32_e32 v104, v34
	v_mov_b32_e32 v105, v34
	v_mov_b32_e32 v106, v34
	v_mov_b32_e32 v107, v34
	v_mov_b32_e32 v112, v34
	v_mov_b32_e32 v113, v34
	v_mov_b32_e32 v114, v34
	v_mov_b32_e32 v115, v34
	v_mov_b32_e32 v120, v34
	v_mov_b32_e32 v121, v34
	v_mov_b32_e32 v122, v34
	v_mov_b32_e32 v123, v34
	v_mov_b32_e32 v128, v34
	v_mov_b32_e32 v129, v34
	v_mov_b32_e32 v130, v34
	v_mov_b32_e32 v131, v34
	v_mov_b32_e32 v136, v34
	v_mov_b32_e32 v137, v34
	v_mov_b32_e32 v138, v34
	v_mov_b32_e32 v139, v34
	v_mov_b32_e32 v144, v34
	v_mov_b32_e32 v145, v34
	v_mov_b32_e32 v146, v34
	v_mov_b32_e32 v147, v34
	v_mov_b32_e32 v152, v34
	v_mov_b32_e32 v153, v34
	v_mov_b32_e32 v154, v34
	v_mov_b32_e32 v155, v34
	v_mov_b32_e32 v160, v34
	v_mov_b32_e32 v161, v34
	v_mov_b32_e32 v162, v34
	v_mov_b32_e32 v163, v34
	s_nop 0
	s_branch .LBB0_2404

;     ...
; #pragma unroll
;         for (int a = 0; a < 2; ++a)
; #pragma unroll
;             for (int b = 0; b < 2; ++b)
; #pragma unroll
;                 for (int m = 0; m < 4; ++m)
; #pragma unroll
;                     for (int n = 0; n < 2; ++n) acc[a][b][m][n] = (f32x4){0.f, 0.f, 0.f, 0.f};
;         cur = nxt; cA = nA; cB = nB; ++ui;
.LBB0_2477:
	s_add_u32 s13, s14, 0x100
	s_addc_u32 s16, s15, 0
	s_add_u32 s48, s2, 0x20080
	v_mov_b32_e32 v68, 0
	s_addc_u32 s49, s3, 0
	s_mov_b32 s17, -2
	v_mov_b32_e32 v69, v68
	v_mov_b32_e32 v70, v68
	v_mov_b32_e32 v71, v68
	v_mov_b32_e32 v72, v68
	v_mov_b32_e32 v73, v68
	v_mov_b32_e32 v74, v68
	v_mov_b32_e32 v75, v68
	s_nop 0
	v_mov_b32_e32 v84, v68
	v_mov_b32_e32 v85, v68
	v_mov_b32_e32 v86, v68
	v_mov_b32_e32 v87, v68
	v_mov_b32_e32 v88, v68
	v_mov_b32_e32 v89, v68
	v_mov_b32_e32 v90, v68
	v_mov_b32_e32 v91, v68
	v_mov_b32_e32 v34, v68
	v_mov_b32_e32 v35, v68
	v_mov_b32_e32 v36, v68
	v_mov_b32_e32 v37, v68
	v_mov_b32_e32 v38, v68
	v_mov_b32_e32 v39, v68
	v_mov_b32_e32 v40, v68
	v_mov_b32_e32 v41, v68
	v_mov_b32_e32 v56, v68
	v_mov_b32_e32 v57, v68
	v_mov_b32_e32 v58, v68
	v_mov_b32_e32 v59, v68
	v_mov_b32_e32 v64, v68
	v_mov_b32_e32 v65, v68
	v_mov_b32_e32 v66, v68
	v_mov_b32_e32 v67, v68
	v_mov_b32_e32 v76, v68
	v_mov_b32_e32 v77, v68
	v_mov_b32_e32 v78, v68
	v_mov_b32_e32 v79, v68
	v_mov_b32_e32 v80, v68
	v_mov_b32_e32 v81, v68
	v_mov_b32_e32 v82, v68
	v_mov_b32_e32 v83, v68
	v_mov_b32_e32 v92, v68
	v_mov_b32_e32 v93, v68
	v_mov_b32_e32 v94, v68
	v_mov_b32_e32 v95, v68
	v_mov_b32_e32 v96, v68
	v_mov_b32_e32 v97, v68
	v_mov_b32_e32 v98, v68
	v_mov_b32_e32 v99, v68
	v_mov_b32_e32 v100, v68
	v_mov_b32_e32 v101, v68
	v_mov_b32_e32 v102, v68
	v_mov_b32_e32 v103, v68
	v_mov_b32_e32 v104, v68
	v_mov_b32_e32 v105, v68
	v_mov_b32_e32 v106, v68
	v_mov_b32_e32 v107, v68
	v_mov_b32_e32 v116, v68
	v_mov_b32_e32 v117, v68
	v_mov_b32_e32 v118, v68
	v_mov_b32_e32 v119, v68
	v_mov_b32_e32 v120, v68
	v_mov_b32_e32 v121, v68
	v_mov_b32_e32 v122, v68
	v_mov_b32_e32 v123, v68
	v_mov_b32_e32 v132, v68
	v_mov_b32_e32 v133, v68
	v_mov_b32_e32 v134, v68
	v_mov_b32_e32 v135, v68
	v_mov_b32_e32 v136, v68
	v_mov_b32_e32 v137, v68
	v_mov_b32_e32 v138, v68
	v_mov_b32_e32 v139, v68
	v_mov_b32_e32 v148, v68
	v_mov_b32_e32 v149, v68
	v_mov_b32_e32 v150, v68
	v_mov_b32_e32 v151, v68
	v_mov_b32_e32 v152, v68
	v_mov_b32_e32 v153, v68
	v_mov_b32_e32 v154, v68
	v_mov_b32_e32 v155, v68
	v_mov_b32_e32 v108, v68
	v_mov_b32_e32 v109, v68
	v_mov_b32_e32 v110, v68
	v_mov_b32_e32 v111, v68
	v_mov_b32_e32 v112, v68
	v_mov_b32_e32 v113, v68
	v_mov_b32_e32 v114, v68
	v_mov_b32_e32 v115, v68
	v_mov_b32_e32 v124, v68
	v_mov_b32_e32 v125, v68
	v_mov_b32_e32 v126, v68
	v_mov_b32_e32 v127, v68
	v_mov_b32_e32 v128, v68
	v_mov_b32_e32 v129, v68
	v_mov_b32_e32 v130, v68
	v_mov_b32_e32 v131, v68
	v_mov_b32_e32 v140, v68
	v_mov_b32_e32 v141, v68
	v_mov_b32_e32 v142, v68
	v_mov_b32_e32 v143, v68
	v_mov_b32_e32 v144, v68
	v_mov_b32_e32 v145, v68
	v_mov_b32_e32 v146, v68
	v_mov_b32_e32 v147, v68
	v_mov_b32_e32 v156, v68
	v_mov_b32_e32 v157, v68
	v_mov_b32_e32 v158, v68
	v_mov_b32_e32 v159, v68
	v_mov_b32_e32 v160, v68
	v_mov_b32_e32 v161, v68
	v_mov_b32_e32 v162, v68
	v_mov_b32_e32 v163, v68
	v_mov_b32_e32 v52, v68
	v_mov_b32_e32 v53, v68
	v_mov_b32_e32 v54, v68
	v_mov_b32_e32 v55, v68
	v_mov_b32_e32 v60, v68
	v_mov_b32_e32 v61, v68
	v_mov_b32_e32 v62, v68
	v_mov_b32_e32 v63, v68
	v_mov_b32_e32 v42, v68
	v_mov_b32_e32 v43, v68
	v_mov_b32_e32 v44, v68
	v_mov_b32_e32 v45, v68
	v_mov_b32_e32 v46, v68
	v_mov_b32_e32 v47, v68
	v_mov_b32_e32 v48, v68
	v_mov_b32_e32 v49, v68
